# P4 compress stage 2: six consecutive rows per wave per pass (w2 column loads shared by six dot products)
# speedup vs baseline: 1.0086x; 1.0007x over previous
.LBB0_645:
	s_or_b64 exec, exec, s[0:1]
	v_mov_b32_e32 v7, 0
	s_waitcnt lgkmcnt(0)
	s_barrier
	v_mov_b32_e32 v0, s44
	v_mov_b32_e32 v1, s45
	v_mov_b32_e32 v6, 0x3308000
	global_load_dwordx2 v[4:5], v6, s[44:45] offset:72
	s_cmpk_gt_i32 s52, 0x7f7
	v_lshrrev_b32_e32 v230, 5, v229
	s_waitcnt vmcnt(1)
	v_readfirstlane_b32 s4, v0
	v_readfirstlane_b32 s5, v1
	s_cbranch_scc1 .LBB0_661
	global_load_dwordx4 v[0:3], v6, s[44:45] offset:136
	global_load_dwordx2 v[12:13], v7, s[6:7]
	s_add_u32 s16, s4, 0x3f00000
	s_addc_u32 s21, s5, 0
	v_lshlrev_b32_e32 v6, 2, v229
	s_add_u32 s22, s4, 0x4600000
	v_lshlrev_b32_e32 v8, 9, v230
	v_lshlrev_b32_e32 v9, 3, v229
	s_movk_i32 s14, 0x3d07
	v_lshlrev_b32_e32 v10, 5, v229
	v_mbcnt_hi_u32_b32 v22, -1, v228
	s_addc_u32 s23, s5, 0
	s_mov_b64 s[2:3], 0x3400000
	v_or3_b32 v8, v8, v9, s14
	v_and_b32_e32 v23, 0x700, v10
	v_or_b32_e32 v10, 0x38f8, v10
	v_and_b32_e32 v9, 64, v22
	s_add_u32 s24, s4, 0x4500000
	v_cmp_lt_u32_e64 s[0:1], 31, v229
	s_mov_b64 s[6:7], 0x1000
	s_movk_i32 s17, 0x7fff
	v_mov_b32_e32 v20, 0x358637bd
	s_mov_b32 s20, 0xf800000
	v_mov_b32_e32 v21, 0x260
	s_mov_b64 s[8:9], 0x1f00
	v_xor_b32_e32 v24, 1, v22
	v_xor_b32_e32 v25, 2, v22
	v_lshlrev_b32_e32 v8, 1, v8
	v_lshlrev_b32_e32 v10, 1, v10
	v_add_u32_e32 v26, 64, v9
	s_addc_u32 s25, s5, 0
	s_mul_i32 s26, s52, 6
	s_add_i32 s86, s26, 6
	s_waitcnt vmcnt(1)
	v_lshl_add_u64 v[0:1], v[0:1], 0, v[6:7]
	s_waitcnt vmcnt(0)
	v_lshl_add_u64 v[12:13], v[12:13], 0, v[6:7]
	v_and_b32_e32 v6, 0xf8, v144
	v_lshl_add_u64 v[14:15], s[4:5], 0, v[6:7]
	v_lshl_add_u64 v[14:15], v[14:15], 0, s[2:3]
	s_mov_b32 s78, 0
	s_branch .LBB0_648
.LBB0_647:
	s_cmp_eq_u32 s78, 0
	s_cbranch_scc1 .Lc3_none
	s_add_i32 s26, s26, 1
	s_sub_i32 s14, s26, s79
	v_mov_b32_e32 v18, 0
	v_mov_b32_e32 v19, 0
	v_mov_b32_e32 v9, 0
	s_cmp_eq_u32 s78, 5
	s_cbranch_scc0 .Lc3_n1
	v_mov_b32_e32 v6, v210
	s_mov_b32 s78, 4
	s_branch .Lc3_epi
.Lc3_n1:
	s_cmp_eq_u32 s78, 4
	s_cbranch_scc0 .Lc3_n2
	v_mov_b32_e32 v6, v211
	s_mov_b32 s78, 3
	s_branch .Lc3_epi
.Lc3_n2:
	s_cmp_eq_u32 s78, 3
	s_cbranch_scc0 .Lc3_n3
	v_mov_b32_e32 v6, v212
	s_mov_b32 s78, 2
	s_branch .Lc3_epi
.Lc3_n3:
	s_cmp_eq_u32 s78, 2
	s_cbranch_scc0 .Lc3_n4
	v_mov_b32_e32 v6, v213
	s_mov_b32 s78, 1
	s_branch .Lc3_epi
.Lc3_n4:
	s_cmp_eq_u32 s78, 1
	s_cbranch_scc0 .Lc3_n5
	v_mov_b32_e32 v6, v214
	s_mov_b32 s78, 0
	s_branch .Lc3_epi
.Lc3_n5:
	s_mov_b32 s78, 0
.Lc3_none:
	s_add_i32 s26, s26, 1
	s_cmp_lt_i32 s26, s86
	s_cbranch_scc0 .LBB0_661
.LBB0_648:
	s_mul_hi_i32 s2, s26, 0x2ad5802b
	s_lshr_b32 s3, s2, 31
	s_ashr_i32 s2, s2, 10
	s_add_i32 s28, s2, s3
	v_lshl_or_b32 v16, s28, 6, v229
	v_ashrrev_i32_e32 v17, 31, v16
	v_lshl_add_u64 v[16:17], v[16:17], 2, v[2:3]
	global_load_dword v6, v[16:17], off
	s_mul_i32 s2, s28, 0x17e8
	s_sub_i32 s14, s26, s2
	s_ashr_i32 s29, s28, 31
	s_mul_i32 s2, s28, 0x1800
	s_ashr_i32 s15, s14, 31
	s_mul_hi_i32 s3, s28, 0x1800
	s_add_u32 s2, s2, s14
	s_addc_u32 s3, s3, s15
	s_lshl_b64 s[2:3], s[2:3], 9
	s_add_u32 s2, s16, s2
	s_addc_u32 s3, s21, s3
	s_lshl_b64 s[28:29], s[28:29], 16
	v_mov_b32_e32 v9, 0
	v_lshl_add_u64 v[16:17], v[0:1], 0, s[28:29]
	s_mov_b32 s15, -2
	v_mov_b32_e32 v18, 0
	v_mov_b32_e32 v19, v9
	s_add_i32 s80, s26, 5
	s_cmp_lt_i32 s80, s86
	s_cbranch_scc0 .Lc3_single
	s_sub_i32 s79, s26, s14
	s_mov_b64 s[60:61], s[2:3]
	s_mov_b64 s[82:83], 0x1000
	v_mov_b32_e32 v167, 0
	v_mov_b32_e32 v178, v16
	v_mov_b32_e32 v179, v17
	global_load_dwordx4 v[84:87], v167, s[60:61]
	global_load_dwordx4 v[88:91], v167, s[60:61] offset:512
	global_load_dwordx4 v[92:95], v167, s[60:61] offset:1024
	global_load_dwordx4 v[96:99], v167, s[60:61] offset:1536
	global_load_dwordx4 v[100:103], v167, s[60:61] offset:2048
	global_load_dwordx4 v[104:107], v167, s[60:61] offset:2560
	global_load_dword v231, v[178:179], off
	global_load_dword v232, v[178:179], off offset:256
	global_load_dword v233, v[178:179], off offset:512
	global_load_dword v234, v[178:179], off offset:768
	global_load_dword v235, v[178:179], off offset:1024
	global_load_dword v236, v[178:179], off offset:1280
	global_load_dword v237, v[178:179], off offset:1536
	global_load_dword v238, v[178:179], off offset:1792
	v_mov_b32_e32 v60, 0
	v_mov_b32_e32 v61, 0
	v_mov_b32_e32 v62, 0
	v_mov_b32_e32 v64, 0
	v_mov_b32_e32 v65, 0
	v_mov_b32_e32 v66, 0
	v_mov_b32_e32 v68, 0
	v_mov_b32_e32 v69, 0
	v_mov_b32_e32 v70, 0
	v_mov_b32_e32 v72, 0
	v_mov_b32_e32 v73, 0
	v_mov_b32_e32 v74, 0
	v_mov_b32_e32 v76, 0
	v_mov_b32_e32 v77, 0
	v_mov_b32_e32 v78, 0
	v_mov_b32_e32 v80, 0
	v_mov_b32_e32 v81, 0
	v_mov_b32_e32 v82, 0
	s_mov_b32 s77, 0
	s_waitcnt vmcnt(14)
	v_mov_b32_e32 v59, v6
	v_mov_b32_e32 v63, v6
	v_mov_b32_e32 v67, v6
	v_mov_b32_e32 v71, v6
	v_mov_b32_e32 v75, v6
	v_mov_b32_e32 v79, v6
.Lc3_loop:
	global_load_dwordx4 v[186:189], v167, s[60:61] offset:16
	global_load_dwordx4 v[190:193], v167, s[60:61] offset:528
	global_load_dwordx4 v[194:197], v167, s[60:61] offset:1040
	global_load_dwordx4 v[198:201], v167, s[60:61] offset:1552
	global_load_dwordx4 v[202:205], v167, s[60:61] offset:2064
	global_load_dwordx4 v[206:209], v167, s[60:61] offset:2576
	global_load_dword v239, v[178:179], off offset:2048
	global_load_dword v240, v[178:179], off offset:2304
	global_load_dword v241, v[178:179], off offset:2560
	global_load_dword v242, v[178:179], off offset:2816
	global_load_dword v243, v[178:179], off offset:3072
	global_load_dword v244, v[178:179], off offset:3328
	global_load_dword v245, v[178:179], off offset:3584
	global_load_dword v246, v[178:179], off offset:3840
	s_waitcnt vmcnt(14)
	v_lshlrev_b32_e32 v247, 16, v84
	v_and_b32_e32 v248, 0xffff0000, v84
	v_fmac_f32_e32 v59, v247, v231
	v_fmac_f32_e32 v60, v248, v232
	v_lshlrev_b32_e32 v249, 16, v88
	v_and_b32_e32 v250, 0xffff0000, v88
	v_fmac_f32_e32 v63, v249, v231
	v_fmac_f32_e32 v64, v250, v232
	v_lshlrev_b32_e32 v247, 16, v92
	v_and_b32_e32 v248, 0xffff0000, v92
	v_fmac_f32_e32 v67, v247, v231
	v_fmac_f32_e32 v68, v248, v232
	v_lshlrev_b32_e32 v249, 16, v96
	v_and_b32_e32 v250, 0xffff0000, v96
	v_fmac_f32_e32 v71, v249, v231
	v_fmac_f32_e32 v72, v250, v232
	v_lshlrev_b32_e32 v247, 16, v100
	v_and_b32_e32 v248, 0xffff0000, v100
	v_fmac_f32_e32 v75, v247, v231
	v_fmac_f32_e32 v76, v248, v232
	v_lshlrev_b32_e32 v249, 16, v104
	v_and_b32_e32 v250, 0xffff0000, v104
	v_fmac_f32_e32 v79, v249, v231
	v_fmac_f32_e32 v80, v250, v232
	v_lshlrev_b32_e32 v247, 16, v85
	v_and_b32_e32 v248, 0xffff0000, v85
	v_fmac_f32_e32 v61, v247, v233
	v_fmac_f32_e32 v62, v248, v234
	v_lshlrev_b32_e32 v249, 16, v89
	v_and_b32_e32 v250, 0xffff0000, v89
	v_fmac_f32_e32 v65, v249, v233
	v_fmac_f32_e32 v66, v250, v234
	v_lshlrev_b32_e32 v247, 16, v93
	v_and_b32_e32 v248, 0xffff0000, v93
	v_fmac_f32_e32 v69, v247, v233
	v_fmac_f32_e32 v70, v248, v234
	v_lshlrev_b32_e32 v249, 16, v97
	v_and_b32_e32 v250, 0xffff0000, v97
	v_fmac_f32_e32 v73, v249, v233
	v_fmac_f32_e32 v74, v250, v234
	v_lshlrev_b32_e32 v247, 16, v101
	v_and_b32_e32 v248, 0xffff0000, v101
	v_fmac_f32_e32 v77, v247, v233
	v_fmac_f32_e32 v78, v248, v234
	v_lshlrev_b32_e32 v249, 16, v105
	v_and_b32_e32 v250, 0xffff0000, v105
	v_fmac_f32_e32 v81, v249, v233
	v_fmac_f32_e32 v82, v250, v234
	v_lshlrev_b32_e32 v247, 16, v86
	v_and_b32_e32 v248, 0xffff0000, v86
	v_fmac_f32_e32 v59, v247, v235
	v_fmac_f32_e32 v60, v248, v236
	v_lshlrev_b32_e32 v249, 16, v90
	v_and_b32_e32 v250, 0xffff0000, v90
	v_fmac_f32_e32 v63, v249, v235
	v_fmac_f32_e32 v64, v250, v236
	v_lshlrev_b32_e32 v247, 16, v94
	v_and_b32_e32 v248, 0xffff0000, v94
	v_fmac_f32_e32 v67, v247, v235
	v_fmac_f32_e32 v68, v248, v236
	v_lshlrev_b32_e32 v249, 16, v98
	v_and_b32_e32 v250, 0xffff0000, v98
	v_fmac_f32_e32 v71, v249, v235
	v_fmac_f32_e32 v72, v250, v236
	v_lshlrev_b32_e32 v247, 16, v102
	v_and_b32_e32 v248, 0xffff0000, v102
	v_fmac_f32_e32 v75, v247, v235
	v_fmac_f32_e32 v76, v248, v236
	v_lshlrev_b32_e32 v249, 16, v106
	v_and_b32_e32 v250, 0xffff0000, v106
	v_fmac_f32_e32 v79, v249, v235
	v_fmac_f32_e32 v80, v250, v236
	v_lshlrev_b32_e32 v247, 16, v87
	v_and_b32_e32 v248, 0xffff0000, v87
	v_fmac_f32_e32 v61, v247, v237
	v_fmac_f32_e32 v62, v248, v238
	v_lshlrev_b32_e32 v249, 16, v91
	v_and_b32_e32 v250, 0xffff0000, v91
	v_fmac_f32_e32 v65, v249, v237
	v_fmac_f32_e32 v66, v250, v238
	v_lshlrev_b32_e32 v247, 16, v95
	v_and_b32_e32 v248, 0xffff0000, v95
	v_fmac_f32_e32 v69, v247, v237
	v_fmac_f32_e32 v70, v248, v238
	v_lshlrev_b32_e32 v249, 16, v99
	v_and_b32_e32 v250, 0xffff0000, v99
	v_fmac_f32_e32 v73, v249, v237
	v_fmac_f32_e32 v74, v250, v238
	v_lshlrev_b32_e32 v247, 16, v103
	v_and_b32_e32 v248, 0xffff0000, v103
	v_fmac_f32_e32 v77, v247, v237
	v_fmac_f32_e32 v78, v248, v238
	v_lshlrev_b32_e32 v249, 16, v107
	v_and_b32_e32 v250, 0xffff0000, v107
	v_fmac_f32_e32 v81, v249, v237
	v_fmac_f32_e32 v82, v250, v238
	s_add_u32 s60, s60, 32
	s_addc_u32 s61, s61, 0
	v_lshl_add_u64 v[178:179], v[178:179], 0, s[82:83]
	s_cmp_eq_u32 s77, 15
	s_cbranch_scc1 .Lc3_last
	global_load_dwordx4 v[84:87], v167, s[60:61]
	global_load_dwordx4 v[88:91], v167, s[60:61] offset:512
	global_load_dwordx4 v[92:95], v167, s[60:61] offset:1024
	global_load_dwordx4 v[96:99], v167, s[60:61] offset:1536
	global_load_dwordx4 v[100:103], v167, s[60:61] offset:2048
	global_load_dwordx4 v[104:107], v167, s[60:61] offset:2560
	global_load_dword v231, v[178:179], off
	global_load_dword v232, v[178:179], off offset:256
	global_load_dword v233, v[178:179], off offset:512
	global_load_dword v234, v[178:179], off offset:768
	global_load_dword v235, v[178:179], off offset:1024
	global_load_dword v236, v[178:179], off offset:1280
	global_load_dword v237, v[178:179], off offset:1536
	global_load_dword v238, v[178:179], off offset:1792
	s_waitcnt vmcnt(14)
	v_lshlrev_b32_e32 v247, 16, v186
	v_and_b32_e32 v248, 0xffff0000, v186
	v_fmac_f32_e32 v59, v247, v239
	v_fmac_f32_e32 v60, v248, v240
	v_lshlrev_b32_e32 v249, 16, v190
	v_and_b32_e32 v250, 0xffff0000, v190
	v_fmac_f32_e32 v63, v249, v239
	v_fmac_f32_e32 v64, v250, v240
	v_lshlrev_b32_e32 v247, 16, v194
	v_and_b32_e32 v248, 0xffff0000, v194
	v_fmac_f32_e32 v67, v247, v239
	v_fmac_f32_e32 v68, v248, v240
	v_lshlrev_b32_e32 v249, 16, v198
	v_and_b32_e32 v250, 0xffff0000, v198
	v_fmac_f32_e32 v71, v249, v239
	v_fmac_f32_e32 v72, v250, v240
	v_lshlrev_b32_e32 v247, 16, v202
	v_and_b32_e32 v248, 0xffff0000, v202
	v_fmac_f32_e32 v75, v247, v239
	v_fmac_f32_e32 v76, v248, v240
	v_lshlrev_b32_e32 v249, 16, v206
	v_and_b32_e32 v250, 0xffff0000, v206
	v_fmac_f32_e32 v79, v249, v239
	v_fmac_f32_e32 v80, v250, v240
	v_lshlrev_b32_e32 v247, 16, v187
	v_and_b32_e32 v248, 0xffff0000, v187
	v_fmac_f32_e32 v61, v247, v241
	v_fmac_f32_e32 v62, v248, v242
	v_lshlrev_b32_e32 v249, 16, v191
	v_and_b32_e32 v250, 0xffff0000, v191
	v_fmac_f32_e32 v65, v249, v241
	v_fmac_f32_e32 v66, v250, v242
	v_lshlrev_b32_e32 v247, 16, v195
	v_and_b32_e32 v248, 0xffff0000, v195
	v_fmac_f32_e32 v69, v247, v241
	v_fmac_f32_e32 v70, v248, v242
	v_lshlrev_b32_e32 v249, 16, v199
	v_and_b32_e32 v250, 0xffff0000, v199
	v_fmac_f32_e32 v73, v249, v241
	v_fmac_f32_e32 v74, v250, v242
	v_lshlrev_b32_e32 v247, 16, v203
	v_and_b32_e32 v248, 0xffff0000, v203
	v_fmac_f32_e32 v77, v247, v241
	v_fmac_f32_e32 v78, v248, v242
	v_lshlrev_b32_e32 v249, 16, v207
	v_and_b32_e32 v250, 0xffff0000, v207
	v_fmac_f32_e32 v81, v249, v241
	v_fmac_f32_e32 v82, v250, v242
	v_lshlrev_b32_e32 v247, 16, v188
	v_and_b32_e32 v248, 0xffff0000, v188
	v_fmac_f32_e32 v59, v247, v243
	v_fmac_f32_e32 v60, v248, v244
	v_lshlrev_b32_e32 v249, 16, v192
	v_and_b32_e32 v250, 0xffff0000, v192
	v_fmac_f32_e32 v63, v249, v243
	v_fmac_f32_e32 v64, v250, v244
	v_lshlrev_b32_e32 v247, 16, v196
	v_and_b32_e32 v248, 0xffff0000, v196
	v_fmac_f32_e32 v67, v247, v243
	v_fmac_f32_e32 v68, v248, v244
	v_lshlrev_b32_e32 v249, 16, v200
	v_and_b32_e32 v250, 0xffff0000, v200
	v_fmac_f32_e32 v71, v249, v243
	v_fmac_f32_e32 v72, v250, v244
	v_lshlrev_b32_e32 v247, 16, v204
	v_and_b32_e32 v248, 0xffff0000, v204
	v_fmac_f32_e32 v75, v247, v243
	v_fmac_f32_e32 v76, v248, v244
	v_lshlrev_b32_e32 v249, 16, v208
	v_and_b32_e32 v250, 0xffff0000, v208
	v_fmac_f32_e32 v79, v249, v243
	v_fmac_f32_e32 v80, v250, v244
	v_lshlrev_b32_e32 v247, 16, v189
	v_and_b32_e32 v248, 0xffff0000, v189
	v_fmac_f32_e32 v61, v247, v245
	v_fmac_f32_e32 v62, v248, v246
	v_lshlrev_b32_e32 v249, 16, v193
	v_and_b32_e32 v250, 0xffff0000, v193
	v_fmac_f32_e32 v65, v249, v245
	v_fmac_f32_e32 v66, v250, v246
	v_lshlrev_b32_e32 v247, 16, v197
	v_and_b32_e32 v248, 0xffff0000, v197
	v_fmac_f32_e32 v69, v247, v245
	v_fmac_f32_e32 v70, v248, v246
	v_lshlrev_b32_e32 v249, 16, v201
	v_and_b32_e32 v250, 0xffff0000, v201
	v_fmac_f32_e32 v73, v249, v245
	v_fmac_f32_e32 v74, v250, v246
	v_lshlrev_b32_e32 v247, 16, v205
	v_and_b32_e32 v248, 0xffff0000, v205
	v_fmac_f32_e32 v77, v247, v245
	v_fmac_f32_e32 v78, v248, v246
	v_lshlrev_b32_e32 v249, 16, v209
	v_and_b32_e32 v250, 0xffff0000, v209
	v_fmac_f32_e32 v81, v249, v245
	v_fmac_f32_e32 v82, v250, v246
	s_add_u32 s77, s77, 1
	s_branch .Lc3_loop
.Lc3_last:
	s_waitcnt vmcnt(0)
	v_lshlrev_b32_e32 v247, 16, v186
	v_and_b32_e32 v248, 0xffff0000, v186
	v_fmac_f32_e32 v59, v247, v239
	v_fmac_f32_e32 v60, v248, v240
	v_lshlrev_b32_e32 v249, 16, v190
	v_and_b32_e32 v250, 0xffff0000, v190
	v_fmac_f32_e32 v63, v249, v239
	v_fmac_f32_e32 v64, v250, v240
	v_lshlrev_b32_e32 v247, 16, v194
	v_and_b32_e32 v248, 0xffff0000, v194
	v_fmac_f32_e32 v67, v247, v239
	v_fmac_f32_e32 v68, v248, v240
	v_lshlrev_b32_e32 v249, 16, v198
	v_and_b32_e32 v250, 0xffff0000, v198
	v_fmac_f32_e32 v71, v249, v239
	v_fmac_f32_e32 v72, v250, v240
	v_lshlrev_b32_e32 v247, 16, v202
	v_and_b32_e32 v248, 0xffff0000, v202
	v_fmac_f32_e32 v75, v247, v239
	v_fmac_f32_e32 v76, v248, v240
	v_lshlrev_b32_e32 v249, 16, v206
	v_and_b32_e32 v250, 0xffff0000, v206
	v_fmac_f32_e32 v79, v249, v239
	v_fmac_f32_e32 v80, v250, v240
	v_lshlrev_b32_e32 v247, 16, v187
	v_and_b32_e32 v248, 0xffff0000, v187
	v_fmac_f32_e32 v61, v247, v241
	v_fmac_f32_e32 v62, v248, v242
	v_lshlrev_b32_e32 v249, 16, v191
	v_and_b32_e32 v250, 0xffff0000, v191
	v_fmac_f32_e32 v65, v249, v241
	v_fmac_f32_e32 v66, v250, v242
	v_lshlrev_b32_e32 v247, 16, v195
	v_and_b32_e32 v248, 0xffff0000, v195
	v_fmac_f32_e32 v69, v247, v241
	v_fmac_f32_e32 v70, v248, v242
	v_lshlrev_b32_e32 v249, 16, v199
	v_and_b32_e32 v250, 0xffff0000, v199
	v_fmac_f32_e32 v73, v249, v241
	v_fmac_f32_e32 v74, v250, v242
	v_lshlrev_b32_e32 v247, 16, v203
	v_and_b32_e32 v248, 0xffff0000, v203
	v_fmac_f32_e32 v77, v247, v241
	v_fmac_f32_e32 v78, v248, v242
	v_lshlrev_b32_e32 v249, 16, v207
	v_and_b32_e32 v250, 0xffff0000, v207
	v_fmac_f32_e32 v81, v249, v241
	v_fmac_f32_e32 v82, v250, v242
	v_lshlrev_b32_e32 v247, 16, v188
	v_and_b32_e32 v248, 0xffff0000, v188
	v_fmac_f32_e32 v59, v247, v243
	v_fmac_f32_e32 v60, v248, v244
	v_lshlrev_b32_e32 v249, 16, v192
	v_and_b32_e32 v250, 0xffff0000, v192
	v_fmac_f32_e32 v63, v249, v243
	v_fmac_f32_e32 v64, v250, v244
	v_lshlrev_b32_e32 v247, 16, v196
	v_and_b32_e32 v248, 0xffff0000, v196
	v_fmac_f32_e32 v67, v247, v243
	v_fmac_f32_e32 v68, v248, v244
	v_lshlrev_b32_e32 v249, 16, v200
	v_and_b32_e32 v250, 0xffff0000, v200
	v_fmac_f32_e32 v71, v249, v243
	v_fmac_f32_e32 v72, v250, v244
	v_lshlrev_b32_e32 v247, 16, v204
	v_and_b32_e32 v248, 0xffff0000, v204
	v_fmac_f32_e32 v75, v247, v243
	v_fmac_f32_e32 v76, v248, v244
	v_lshlrev_b32_e32 v249, 16, v208
	v_and_b32_e32 v250, 0xffff0000, v208
	v_fmac_f32_e32 v79, v249, v243
	v_fmac_f32_e32 v80, v250, v244
	v_lshlrev_b32_e32 v247, 16, v189
	v_and_b32_e32 v248, 0xffff0000, v189
	v_fmac_f32_e32 v61, v247, v245
	v_fmac_f32_e32 v62, v248, v246
	v_lshlrev_b32_e32 v249, 16, v193
	v_and_b32_e32 v250, 0xffff0000, v193
	v_fmac_f32_e32 v65, v249, v245
	v_fmac_f32_e32 v66, v250, v246
	v_lshlrev_b32_e32 v247, 16, v197
	v_and_b32_e32 v248, 0xffff0000, v197
	v_fmac_f32_e32 v69, v247, v245
	v_fmac_f32_e32 v70, v248, v246
	v_lshlrev_b32_e32 v249, 16, v201
	v_and_b32_e32 v250, 0xffff0000, v201
	v_fmac_f32_e32 v73, v249, v245
	v_fmac_f32_e32 v74, v250, v246
	v_lshlrev_b32_e32 v247, 16, v205
	v_and_b32_e32 v248, 0xffff0000, v205
	v_fmac_f32_e32 v77, v247, v245
	v_fmac_f32_e32 v78, v248, v246
	v_lshlrev_b32_e32 v249, 16, v209
	v_and_b32_e32 v250, 0xffff0000, v209
	v_fmac_f32_e32 v81, v249, v245
	v_fmac_f32_e32 v82, v250, v246
	v_add_f32_e32 v59, v59, v60
	v_add_f32_e32 v61, v61, v62
	v_add_f32_e32 v6, v59, v61
	v_add_f32_e32 v63, v63, v64
	v_add_f32_e32 v65, v65, v66
	v_add_f32_e32 v210, v63, v65
	v_add_f32_e32 v67, v67, v68
	v_add_f32_e32 v69, v69, v70
	v_add_f32_e32 v211, v67, v69
	v_add_f32_e32 v71, v71, v72
	v_add_f32_e32 v73, v73, v74
	v_add_f32_e32 v212, v71, v73
	v_add_f32_e32 v75, v75, v76
	v_add_f32_e32 v77, v77, v78
	v_add_f32_e32 v213, v75, v77
	v_add_f32_e32 v79, v79, v80
	v_add_f32_e32 v81, v81, v82
	v_add_f32_e32 v214, v79, v81
	v_mov_b32_e32 v18, 0
	v_mov_b32_e32 v19, 0
	v_mov_b32_e32 v9, 0
	s_mov_b32 s78, 5
	s_branch .Lc3_epi
